# v62 with the whole kernel shifted by 8 bytes (two s_nop at entry): code placement
# speedup vs baseline: 1.0081x; 1.0081x over previous
_Z4mega6Params:
	s_nop 0
	s_nop 0
	s_mov_b64 s[96:97], s[0:1]
	s_load_dword s70, s[96:97], 0x100
	s_load_dwordx2 s[30:31], s[96:97], 0xa8
	s_add_u32 s0, s96, 0x100
	s_addc_u32 s1, s97, 0
	v_and_b32_e32 v1, 0x3ff, v0
	v_writelane_b32 v251, s0, 0
	s_mov_b32 s67, s2
	v_readfirstlane_b32 s2, v1
	v_writelane_b32 v251, s1, 1
	v_cmp_gt_u32_e32 vcc, 4, v1
	s_and_saveexec_b64 s[0:1], vcc
	v_lshl_add_u32 v2, v1, 2, 0
	v_add_u32_e32 v2, 0x23ff0, v2
	v_mov_b32_e32 v3, 0
	ds_write_b32 v2, v3
	s_or_b64 exec, exec, s[0:1]
	s_load_dwordx2 s[48:49], s[96:97], 0xf8
	s_waitcnt lgkmcnt(0)
	s_barrier
	s_add_u32 s12, s30, 0x2d608000
	s_getreg_b32 s0, hwreg(HW_REG_XCC_ID, 0, 4)
	s_addc_u32 s13, s31, 0
	s_and_b32 s36, s0, 15
	v_cmp_eq_u32_e64 s[4:5], 0, v1
	s_mov_b64 s[0:1], exec
	s_nop 0
	v_writelane_b32 v251, s4, 2
	s_nop 1
	v_writelane_b32 v251, s5, 3
	s_and_b64 s[4:5], s[0:1], s[4:5]
	s_mov_b64 exec, s[4:5]
	s_cbranch_execz .LBB0_5
	s_mov_b64 s[4:5], exec
	v_mbcnt_lo_u32_b32 v2, s4, 0
	v_mbcnt_hi_u32_b32 v2, s5, v2
	v_cmp_eq_u32_e32 vcc, 0, v2
	s_and_b64 s[6:7], exec, vcc
	s_mov_b64 exec, s[6:7]
	s_cbranch_execz .LBB0_5
	s_lshl_b32 s3, s36, 8
	s_bcnt1_i32_b64 s4, s[4:5]
	v_mov_b32_e32 v2, s3
	v_mov_b32_e32 v3, s4
	global_atomic_add v2, v3, s[12:13] offset:1024
